# token-mixing phase: one static s_setprio 1 for waves 0-3 (older half, state owners in the scans) at phase entry, reset at exit
# speedup vs baseline: 1.0055x; 1.0055x over previous
; __device__ __forceinline__ void phase_mix(const Frame& F, ArgsRef A, int l, bool last) {
;     unsigned long long tp = (MK_PROBE & 0x700) ? __builtin_amdgcn_s_memrealtime() : 0ull;
;     ...
;     for (int v = F.bid; v < 256; v += F.G) rwkv_chunk_item(F, A, l, ((v & 7) << 5) | (v >> 3), last);
.LBB0_760:
	s_or_b64 exec, exec, s[0:1]
	s_mov_b32 s2, s95
	s_mov_b32 s82, s93
	s_mov_b32 s10, s50
	s_mov_b32 s0, s92
	s_waitcnt lgkmcnt(0)
	s_barrier
	s_cmp_lt_u32 s95, 4
	s_cbranch_scc0 .Lp7_prio_done
	s_setprio 1
